# adds: attention unit staging waits count the previous unit's 5 output stores (vmcnt 10..5 for non-first units), so staging no longer stalls until those stores complete
# baseline (speedup 1.0000x reference)
; #define LAS __attribute__((address_space(3)))
; DI void lbar() { asm volatile("s_waitcnt lgkmcnt(0)" ::: "memory"); __builtin_amdgcn_s_barrier(); asm volatile("" ::: "memory"); }
; DI void attn_phase(LAS unsigned char* lds, bf16_t* QKV, float* LSE, const float* qg, const float* kg, const float* relb, int G, int bid) {
;     ...
; #pragma unroll
;         for (int it = 0; it < 2; ++it) { const int idx = tid + 512 * it, row = idx >> 3, pc = idx & 7;
;             *(LAS u32x4*)(Qs + row * 72 + pc * 8) = pq[it];
;             *(LAS u32x4*)(Ks + (slot * 128 + row) * 72 + pc * 8) = pk[it]; }
;         vt_store(Vt32 + (8 * vpc) * 132 + slot * 64 + kp2, pv[0], pv[1]);
;         lbar();
;         if (u + 1 < u1) {
;             int rn2, h2, g2, d2, n2; size_t rb2; attn_unit_ptrs(u + 1, rn2, h2, g2, d2, n2, rb2);
;             const bf16_t* qp2 = QKV + (size_t)g2 * SEC + rb2 * 1024 + h2 * 64; const bf16_t* kp2p = qp2 + 3 * SEC; const bf16_t* vp2 = qp2 + 6 * SEC;
; #pragma unroll
;             for (int it = 0; it < 2; ++it) { const int idx = tid + 512 * it, row = idx >> 3, pc = idx & 7; pq[it] = *(const u32x4*)(qp2 + (size_t)row * 1024 + pc * 8); pk[it] = *(const u32x4*)(kp2p + (size_t)row * 1024 + pc * 8); }
;             pv[0] = *(const u32x4*)(vp2 + (size_t)(2 * kp2) * 1024 + vpc * 8); pv[1] = *(const u32x4*)(vp2 + (size_t)(2 * kp2 + 1) * 1024 + vpc * 8);
.LBB0_326:
	s_lshl_b32 s83, s82, 7
	v_add_u32_e32 v57, s83, v26
	v_mad_u64_u32 v[110:111], s[88:89], v57, s25, v[40:41]
	v_add_u32_e32 v57, s83, v30
	s_cmp_eq_u32 s87, 0
	s_cbranch_scc1 .Lat_first
	s_waitcnt vmcnt(10)
	ds_write_b128 v119, v[0:3]
	s_waitcnt vmcnt(9)
	ds_write_b128 v110, v[4:7] offset:18432
	s_waitcnt vmcnt(8)
	ds_write_b128 v120, v[8:11]
	v_mad_u64_u32 v[110:111], s[88:89], v57, s25, v[40:41]
	s_waitcnt vmcnt(7)
	ds_write_b128 v110, v[12:15] offset:18432
	v_lshl_add_u32 v57, s82, 8, v42
	s_waitcnt vmcnt(5)
	s_branch .Lat_join
.Lat_first:
	s_waitcnt vmcnt(5)
	ds_write_b128 v119, v[0:3]
	s_waitcnt vmcnt(4)
	ds_write_b128 v110, v[4:7] offset:18432
	s_waitcnt vmcnt(3)
	ds_write_b128 v120, v[8:11]
	v_mad_u64_u32 v[110:111], s[88:89], v57, s25, v[40:41]
	s_waitcnt vmcnt(2)
	ds_write_b128 v110, v[12:15] offset:18432
	v_lshl_add_u32 v57, s82, 8, v42
	s_waitcnt vmcnt(0)
.Lat_join:
	v_lshlrev_b32_e32 v110, 16, v20
	s_mov_b32 s82, 0xffff
	v_lshrrev_b32_e32 v111, 16, v16
	v_and_or_b32 v110, v16, s82, v110
	v_and_or_b32 v111, v20, s27, v111
	v_add_u32_e32 v112, 0xd800, v57
	ds_write2_b32 v112, v110, v111 offset1:132
	v_lshlrev_b32_e32 v110, 16, v21
	v_lshrrev_b32_e32 v111, 16, v17
	v_and_or_b32 v110, v17, s82, v110
	v_and_or_b32 v111, v21, s27, v111
	v_add_u32_e32 v112, 0xdc00, v57
	ds_write2_b32 v112, v110, v111 offset0:8 offset1:140
	v_lshlrev_b32_e32 v110, 16, v22
	v_lshrrev_b32_e32 v111, 16, v18
	v_and_or_b32 v110, v18, s82, v110
	v_and_or_b32 v111, v22, s27, v111
	v_add_u32_e32 v112, 0xe000, v57
	ds_write2_b32 v112, v110, v111 offset0:16 offset1:148
	v_lshlrev_b32_e32 v110, 16, v23
	v_lshrrev_b32_e32 v111, 16, v19
	v_and_or_b32 v110, v19, s82, v110
	v_and_or_b32 v111, v23, s27, v111
	v_add_u32_e32 v57, 0xe400, v57
	ds_write2_b32 v57, v110, v111 offset0:24 offset1:156
	s_waitcnt lgkmcnt(0)
	s_barrier
	s_add_i32 s2, s2, 1
	v_readlane_b32 s82, v251, 24
	s_cmp_ge_i32 s2, s82
	s_cbranch_scc1 .LBB0_328
	s_ashr_i32 s82, s2, 10
	s_mul_hi_i32 s83, s82, 0x55555556
	s_lshr_b32 s88, s83, 31
	s_add_i32 s83, s83, s88
	s_and_b32 s90, s2, 0x3c0
	s_mul_i32 s83, s83, 3
	s_mul_hi_i32 s2, s2, 0x2aaaaaab
	s_sub_i32 s82, s82, s83
	s_lshr_b32 s83, s2, 31
	s_lshr_b32 s2, s2, 9
	s_add_i32 s2, s2, s83
	s_add_i32 s83, s78, 0x80
	s_lshl_b32 s2, s2, 13
	s_and_b32 s83, s83, 0x1f80
	s_or_b32 s88, s83, s2
	s_ashr_i32 s83, s82, 31
	s_ashr_i32 s89, s88, 31
	s_lshl_b64 s[82:83], s[82:83], 25
	s_add_u32 s2, s28, s82
	s_addc_u32 s91, s29, s83
	s_lshl_b64 s[82:83], s[88:89], 11
	s_add_u32 s2, s2, s82
	s_addc_u32 s83, s91, s83
	s_lshl_b32 s82, s90, 1
	s_add_u32 s82, s2, s82
	s_addc_u32 s83, s83, 0
	v_lshlrev_b32_e32 v112, 1, v24
	v_lshl_add_u64 v[8:9], s[82:83], 0, v[112:113]
	v_lshlrev_b32_e32 v112, 1, v34
	v_lshl_add_u64 v[16:17], s[82:83], 0, v[112:113]
	s_mov_b64 s[88:89], 0x6000000
	v_lshl_add_u64 v[16:17], v[36:37], 1, v[16:17]
	s_mov_b64 s[82:83], 0xc000000
	v_lshl_add_u64 v[10:11], v[8:9], 0, s[88:89]
	v_lshl_add_u64 v[20:21], v[16:17], 0, s[82:83]
	v_add_co_u32_e32 v16, vcc, 0xc000000, v16
	v_lshl_add_u64 v[0:1], v[8:9], 0, v[52:53]
	v_lshl_add_u64 v[4:5], v[10:11], 0, v[52:53]
	v_lshl_add_u64 v[8:9], v[8:9], 0, v[54:55]
	v_lshl_add_u64 v[12:13], v[10:11], 0, v[54:55]
	v_addc_co_u32_e32 v17, vcc, 0, v17, vcc
	global_load_dwordx4 v[0:3], v[0:1], off
	s_nop 0
	global_load_dwordx4 v[4:7], v[4:5], off
	s_nop 0
	global_load_dwordx4 v[8:11], v[8:9], off
	s_nop 0
	global_load_dwordx4 v[12:15], v[12:13], off
	s_nop 0
	global_load_dwordx4 v[16:19], v[16:17], off
	s_nop 0
	global_load_dwordx4 v[20:23], v[20:21], off offset:2048
